# scan consumers stage 1: all 16 LDS fragment reads issued up front (v160-223) with counted lgkmcnt waits; dead accumulator zero-fill removed; hazard pad skipped on the real path
# speedup vs baseline: 1.0155x; 1.0020x over previous
.LBB0_387:
	s_andn2_b32 s89, 1, s87
	s_mul_i32 s72, s89, 0xa400
	s_add_i32 s88, s72, 0
	s_and_b64 vcc, exec, s[0:1]
	s_cbranch_vccz .LBB0_394
	s_andn2_b64 vcc, exec, s[68:69]
	s_cbranch_vccnz .LBB0_390
	v_lshlrev_b32_e32 v34, 1, v85
	v_add3_u32 v118, s88, v84, v34
	ds_read_b128 v[160:163], v118
	ds_read_b128 v[164:167], v109
	ds_read_b128 v[168:171], v118 offset:32
	ds_read_b128 v[172:175], v109 offset:32
	ds_read_b128 v[176:179], v118 offset:64
	ds_read_b128 v[180:183], v109 offset:64
	ds_read_b128 v[184:187], v118 offset:96
	ds_read_b128 v[188:191], v109 offset:96
	ds_read_b128 v[192:195], v118 offset:128
	ds_read_b128 v[196:199], v109 offset:128
	ds_read_b128 v[200:203], v118 offset:160
	ds_read_b128 v[204:207], v109 offset:160
	ds_read_b128 v[208:211], v118 offset:192
	ds_read_b128 v[212:215], v109 offset:192
	s_waitcnt lgkmcnt(12)
	v_mfma_f32_32x32x16_bf16 v[50:65], v[160:163], v[164:167], 0
	ds_read_b128 v[216:219], v118 offset:224
	ds_read_b128 v[220:223], v109 offset:224
	s_waitcnt lgkmcnt(12)
	v_mfma_f32_32x32x16_bf16 v[34:49], v[168:171], v[172:175], 0
	s_waitcnt lgkmcnt(10)
	v_mfma_f32_32x32x16_bf16 v[50:65], v[176:179], v[180:183], v[50:65]
	s_waitcnt lgkmcnt(8)
	v_mfma_f32_32x32x16_bf16 v[34:49], v[184:187], v[188:191], v[34:49]
	s_waitcnt lgkmcnt(6)
	v_mfma_f32_32x32x16_bf16 v[50:65], v[192:195], v[196:199], v[50:65]
	s_waitcnt lgkmcnt(4)
	v_mfma_f32_32x32x16_bf16 v[34:49], v[200:203], v[204:207], v[34:49]
	s_waitcnt lgkmcnt(2)
	v_mfma_f32_32x32x16_bf16 v[50:65], v[208:211], v[212:215], v[50:65]
	s_waitcnt lgkmcnt(0)
	v_mfma_f32_32x32x16_bf16 v[34:49], v[216:219], v[220:223], v[34:49]

.Lmy_sc_s88_wb0:
	v_lshlrev_b32_e32 v34, 1, v87
	v_lshlrev_b32_e32 v35, 1, v85
	v_add3_u32 v126, s88, v34, v35
	ds_read_b128 v[160:163], v126 offset:17408
	ds_read_b128 v[164:167], v126 offset:8704
	ds_read_b128 v[168:171], v126 offset:17440
	ds_read_b128 v[172:175], v126 offset:8736
	ds_read_b128 v[176:179], v126 offset:17472
	ds_read_b128 v[180:183], v126 offset:8768
	ds_read_b128 v[184:187], v126 offset:17504
	ds_read_b128 v[188:191], v126 offset:8800
	ds_read_b128 v[192:195], v126 offset:17536
	ds_read_b128 v[196:199], v126 offset:8832
	ds_read_b128 v[200:203], v126 offset:17568
	ds_read_b128 v[204:207], v126 offset:8864
	ds_read_b128 v[208:211], v126 offset:17600
	ds_read_b128 v[212:215], v126 offset:8896
	s_waitcnt lgkmcnt(12)
	v_mfma_f32_32x32x16_bf16 v[50:65], v[160:163], v[164:167], 0
	ds_read_b128 v[216:219], v126 offset:17632
	ds_read_b128 v[220:223], v126 offset:8928
	s_waitcnt lgkmcnt(12)
	v_mfma_f32_32x32x16_bf16 v[34:49], v[168:171], v[172:175], 0
	s_waitcnt lgkmcnt(10)
	v_mfma_f32_32x32x16_bf16 v[50:65], v[176:179], v[180:183], v[50:65]
	s_waitcnt lgkmcnt(8)
	v_mfma_f32_32x32x16_bf16 v[34:49], v[184:187], v[188:191], v[34:49]
	s_waitcnt lgkmcnt(6)
	v_mfma_f32_32x32x16_bf16 v[50:65], v[192:195], v[196:199], v[50:65]
	s_waitcnt lgkmcnt(4)
	v_mfma_f32_32x32x16_bf16 v[34:49], v[200:203], v[204:207], v[34:49]
	s_waitcnt lgkmcnt(2)
	v_mfma_f32_32x32x16_bf16 v[50:65], v[208:211], v[212:215], v[50:65]
	s_waitcnt lgkmcnt(0)
	v_mfma_f32_32x32x16_bf16 v[34:49], v[216:219], v[220:223], v[34:49]
	s_nop 11
	v_add_f32_e32 v110, v50, v34
	v_cndmask_b32_e64 v124, v110, 0, s[4:5]
	v_add_f32_e32 v110, v51, v35
	v_cndmask_b32_e64 v125, v110, 0, s[6:7]
	v_pk_add_f32 v[110:111], v[64:65], v[48:49]
	v_pk_add_f32 v[112:113], v[62:63], v[46:47]
	v_pk_add_f32 v[114:115], v[60:61], v[44:45]
	v_pk_add_f32 v[116:117], v[58:59], v[42:43]
	v_pk_add_f32 v[118:119], v[56:57], v[40:41]
	v_pk_add_f32 v[120:121], v[54:55], v[38:39]
	v_pk_add_f32 v[122:123], v[52:53], v[36:37]
	v_cvt_pk_bf16_f32 v120, v120, v121
	v_cvt_pk_bf16_f32 v122, v122, v123
	v_cvt_pk_bf16_f32 v118, v118, v119
	v_cvt_pk_bf16_f32 v116, v116, v117
	v_cvt_pk_bf16_f32 v114, v114, v115
	v_cvt_pk_bf16_f32 v112, v112, v113
	v_cvt_pk_bf16_f32 v110, v110, v111
	v_cndmask_b32_e64 v123, v122, 0, s[10:11]
	v_lshrrev_b32_e32 v122, 16, v122
	v_cndmask_b32_e64 v121, v120, 0, s[14:15]
	v_lshrrev_b32_e32 v120, 16, v120
	v_cndmask_b32_e64 v119, v118, 0, s[18:19]
	v_lshrrev_b32_e32 v118, 16, v118
	v_cndmask_b32_e64 v117, v116, 0, s[22:23]
	v_lshrrev_b32_e32 v116, 16, v116
	v_cndmask_b32_e64 v115, v114, 0, s[26:27]
	v_lshrrev_b32_e32 v114, 16, v114
	v_cndmask_b32_e64 v113, v112, 0, s[30:31]
	v_lshrrev_b32_e32 v112, 16, v112
	v_cndmask_b32_e64 v111, v110, 0, s[36:37]
	v_lshrrev_b32_e32 v110, 16, v110
	v_cndmask_b32_e64 v122, v122, 0, s[8:9]
	v_cndmask_b32_e64 v120, v120, 0, s[12:13]
	v_cndmask_b32_e64 v118, v118, 0, s[16:17]
	v_cndmask_b32_e64 v116, v116, 0, s[20:21]
	v_cndmask_b32_e64 v114, v114, 0, s[24:25]
	v_cndmask_b32_e64 v112, v112, 0, s[28:29]
	v_cndmask_b32_e64 v110, v110, 0, s[34:35]
	v_cvt_pk_bf16_f32 v124, v124, v125
	v_perm_b32 v125, v122, v123, s3
	v_add_u32_e32 v122, v89, v92
	v_perm_b32 v120, v120, v121, s3
	v_perm_b32 v121, v118, v119, s3
	v_perm_b32 v116, v116, v117, s3
	v_perm_b32 v117, v114, v115, s3
	v_perm_b32 v112, v112, v113, s3
	v_perm_b32 v113, v110, v111, s3
	ds_write_b64 v122, v[124:125]
	ds_write_b64 v93, v[120:121]
	ds_write_b64 v94, v[116:117]
	ds_write_b64 v95, v[112:113]

.LBB0_418:
	s_and_b32 s95, s1, 1
	s_mul_i32 s86, s95, 0xa400
	s_add_i32 s86, s86, 0
	s_and_b64 vcc, exec, s[68:69]
	s_cbranch_vccz .LBB0_425
	s_andn2_b64 vcc, exec, s[70:71]
	s_cbranch_vccnz .LBB0_421
	v_lshlrev_b32_e32 v34, 1, v85
	v_add3_u32 v118, s86, v84, v34
	ds_read_b128 v[160:163], v118
	ds_read_b128 v[164:167], v109
	ds_read_b128 v[168:171], v118 offset:32
	ds_read_b128 v[172:175], v109 offset:32
	ds_read_b128 v[176:179], v118 offset:64
	ds_read_b128 v[180:183], v109 offset:64
	ds_read_b128 v[184:187], v118 offset:96
	ds_read_b128 v[188:191], v109 offset:96
	ds_read_b128 v[192:195], v118 offset:128
	ds_read_b128 v[196:199], v109 offset:128
	ds_read_b128 v[200:203], v118 offset:160
	ds_read_b128 v[204:207], v109 offset:160
	ds_read_b128 v[208:211], v118 offset:192
	ds_read_b128 v[212:215], v109 offset:192
	s_waitcnt lgkmcnt(12)
	v_mfma_f32_32x32x16_bf16 v[50:65], v[160:163], v[164:167], 0
	ds_read_b128 v[216:219], v118 offset:224
	ds_read_b128 v[220:223], v109 offset:224
	s_waitcnt lgkmcnt(12)
	v_mfma_f32_32x32x16_bf16 v[34:49], v[168:171], v[172:175], 0
	s_waitcnt lgkmcnt(10)
	v_mfma_f32_32x32x16_bf16 v[50:65], v[176:179], v[180:183], v[50:65]
	s_waitcnt lgkmcnt(8)
	v_mfma_f32_32x32x16_bf16 v[34:49], v[184:187], v[188:191], v[34:49]
	s_waitcnt lgkmcnt(6)
	v_mfma_f32_32x32x16_bf16 v[50:65], v[192:195], v[196:199], v[50:65]
	s_waitcnt lgkmcnt(4)
	v_mfma_f32_32x32x16_bf16 v[34:49], v[200:203], v[204:207], v[34:49]
	s_waitcnt lgkmcnt(2)
	v_mfma_f32_32x32x16_bf16 v[50:65], v[208:211], v[212:215], v[50:65]
	s_waitcnt lgkmcnt(0)
	v_mfma_f32_32x32x16_bf16 v[34:49], v[216:219], v[220:223], v[34:49]

.Lmy_sc_s86_wb0:
	v_lshlrev_b32_e32 v34, 1, v87
	v_add3_u32 v111, s86, v34, v110
	ds_read_b128 v[160:163], v111 offset:17408
	ds_read_b128 v[164:167], v111 offset:8704
	ds_read_b128 v[168:171], v111 offset:17440
	ds_read_b128 v[172:175], v111 offset:8736
	ds_read_b128 v[176:179], v111 offset:17472
	ds_read_b128 v[180:183], v111 offset:8768
	ds_read_b128 v[184:187], v111 offset:17504
	ds_read_b128 v[188:191], v111 offset:8800
	ds_read_b128 v[192:195], v111 offset:17536
	ds_read_b128 v[196:199], v111 offset:8832
	ds_read_b128 v[200:203], v111 offset:17568
	ds_read_b128 v[204:207], v111 offset:8864
	ds_read_b128 v[208:211], v111 offset:17600
	ds_read_b128 v[212:215], v111 offset:8896
	s_waitcnt lgkmcnt(12)
	v_mfma_f32_32x32x16_bf16 v[50:65], v[160:163], v[164:167], 0
	ds_read_b128 v[216:219], v111 offset:17632
	ds_read_b128 v[220:223], v111 offset:8928
	s_waitcnt lgkmcnt(12)
	v_mfma_f32_32x32x16_bf16 v[34:49], v[168:171], v[172:175], 0
	s_waitcnt lgkmcnt(10)
	v_mfma_f32_32x32x16_bf16 v[50:65], v[176:179], v[180:183], v[50:65]
	s_waitcnt lgkmcnt(8)
	v_mfma_f32_32x32x16_bf16 v[34:49], v[184:187], v[188:191], v[34:49]
	s_waitcnt lgkmcnt(6)
	v_mfma_f32_32x32x16_bf16 v[50:65], v[192:195], v[196:199], v[50:65]
	s_waitcnt lgkmcnt(4)
	v_mfma_f32_32x32x16_bf16 v[34:49], v[200:203], v[204:207], v[34:49]
	s_waitcnt lgkmcnt(2)
	v_mfma_f32_32x32x16_bf16 v[50:65], v[208:211], v[212:215], v[50:65]
	s_waitcnt lgkmcnt(0)
	v_mfma_f32_32x32x16_bf16 v[34:49], v[216:219], v[220:223], v[34:49]
	s_nop 11
	v_add_f32_e32 v111, v50, v34
	v_add_f32_e32 v112, v51, v35
	v_cndmask_b32_e64 v111, v111, 0, s[38:39]
	v_cndmask_b32_e64 v126, 0, v112, s[4:5]
	v_pk_add_f32 v[124:125], v[52:53], v[36:37]
	v_cvt_pk_bf16_f32 v126, v111, v126
	v_cvt_pk_bf16_f32 v111, v124, v125
	v_cndmask_b32_e64 v124, v111, 0, s[42:43]
	v_lshrrev_b32_e32 v111, 16, v111
	v_cndmask_b32_e64 v111, v111, 0, s[40:41]
	v_pk_add_f32 v[122:123], v[54:55], v[38:39]
	v_perm_b32 v127, v111, v124, s3
	v_add_u32_e32 v111, v89, v92
	ds_write_b64 v111, v[126:127]
	v_cvt_pk_bf16_f32 v111, v122, v123
	v_cndmask_b32_e64 v122, v111, 0, s[46:47]
	v_lshrrev_b32_e32 v111, 16, v111
	v_pk_add_f32 v[120:121], v[56:57], v[40:41]
	v_cndmask_b32_e64 v111, v111, 0, s[44:45]
	v_perm_b32 v122, v111, v122, s3
	v_cvt_pk_bf16_f32 v111, v120, v121
	v_cndmask_b32_e64 v120, v111, 0, s[50:51]
	v_lshrrev_b32_e32 v111, 16, v111
	v_pk_add_f32 v[118:119], v[58:59], v[42:43]
	v_cndmask_b32_e64 v111, v111, 0, s[48:49]
	v_perm_b32 v123, v111, v120, s3
	v_cvt_pk_bf16_f32 v111, v118, v119
	v_cndmask_b32_e64 v118, v111, 0, s[54:55]
	v_lshrrev_b32_e32 v111, 16, v111
	v_pk_add_f32 v[116:117], v[60:61], v[44:45]
	v_cndmask_b32_e64 v111, v111, 0, s[52:53]
	v_perm_b32 v118, v111, v118, s3
	v_cvt_pk_bf16_f32 v111, v116, v117
	v_cndmask_b32_e64 v116, v111, 0, s[58:59]
	v_lshrrev_b32_e32 v111, 16, v111
	v_pk_add_f32 v[114:115], v[62:63], v[46:47]
	v_cndmask_b32_e64 v111, v111, 0, s[56:57]
	v_perm_b32 v119, v111, v116, s3
	v_cvt_pk_bf16_f32 v111, v114, v115
	v_cndmask_b32_e64 v114, v111, 0, s[62:63]
	v_lshrrev_b32_e32 v111, 16, v111
	v_pk_add_f32 v[112:113], v[64:65], v[48:49]
	v_cndmask_b32_e64 v111, v111, 0, s[60:61]
	v_perm_b32 v114, v111, v114, s3
	v_cvt_pk_bf16_f32 v111, v112, v113
	v_cndmask_b32_e64 v112, v111, 0, s[66:67]
	v_lshrrev_b32_e32 v111, 16, v111
	v_cndmask_b32_e64 v111, v111, 0, s[64:65]
	v_perm_b32 v115, v111, v112, s3
	ds_write_b64 v93, v[122:123]
	ds_write_b64 v94, v[118:119]
	ds_write_b64 v95, v[114:115]
